# per-unit tile scheduler: runtime-guarded fast path (gridDim.x==256: next unit = same row tile, column tile + 4) skips the two integer divisions before every tile; original code kept as fallback
# speedup vs baseline: 1.0070x; 1.0026x over previous
;     __host__ __device__ bool next(int i, Unit& u) const {
;         const long L = (long)i * G + c; if (L >= nwg) return false;
;         int wgid = (int)L; { const int q = nwg / NXCD, r = nwg % NXCD, xcd = wgid % NXCD, off = wgid / NXCD; wgid = (xcd < r ? xcd * (q + 1) : r * (q + 1) + (xcd - r) * q) + off; }
;         const int nig = WGM * nN, gid = wgid / nig, fm = gid * WGM, gsz = (nM - fm) < WGM ? (nM - fm) : WGM;
;         u.pm = fm + ((wgid % nig) % gsz); u.pn = (wgid % nig) / gsz; return true;
;     }
.LBB0_82:
	s_add_i32 s35, s35, 1
	s_mul_i32 s2, s35, s75
	s_mul_hi_u32 s3, s35, s74
	s_add_i32 s3, s3, s2
	s_mul_i32 s2, s35, s74
	s_add_u32 s12, s2, s24
	s_addc_u32 s13, s3, s26
	v_cmp_gt_i64_e32 vcc, s[12:13], v[144:145]
	v_cmp_lt_i64_e64 s[2:3], s[12:13], v[142:143]
	s_cbranch_vccnz .LBB0_84
	s_cmp_eq_u32 s74, 0x100
	s_cbranch_scc0 .Lsched_slow_0
	s_mov_b32 s10, s16
	s_add_i32 s8, s17, 4
	s_branch .LBB0_84
.Lsched_slow_0:
	s_ashr_i32 s8, s12, 31
	s_lshr_b32 s8, s8, 29
	s_add_i32 s8, s12, s8
	s_ashr_i32 s9, s8, 3
	s_and_b32 s8, s8, -8
	s_sub_i32 s8, s12, s8
	s_cmp_lt_i32 s8, 0
	s_movk_i32 s10, 0x161
	s_cselect_b32 s10, s10, 0x160
	s_mul_i32 s8, s8, s10
	s_add_i32 s8, s8, s9
	s_mul_hi_i32 s9, s8, 0x2e8ba2e9
	s_lshr_b32 s10, s9, 31
	s_ashr_i32 s9, s9, 6
	s_add_i32 s9, s9, s10
	s_lshl_b32 s10, s9, 3
	s_sub_i32 s11, 64, s10
	s_min_i32 s11, s11, 8
	s_abs_i32 s12, s11
	v_cvt_f32_u32_e32 v4, s12
	s_sub_i32 s14, 0, s12
	s_mulk_i32 s9, 0x160
	s_sub_i32 s9, s8, s9
	v_rcp_iflag_f32_e32 v4, v4
	s_abs_i32 s8, s9
	s_xor_b32 s13, s9, s11
	s_ashr_i32 s13, s13, 31
	v_mul_f32_e32 v4, 0x4f7ffffe, v4
	v_cvt_u32_f32_e32 v4, v4
	s_nop 0
	v_readfirstlane_b32 s15, v4
	s_mul_i32 s14, s14, s15
	s_mul_hi_u32 s14, s15, s14
	s_add_i32 s15, s15, s14
	s_mul_hi_u32 s14, s8, s15
	s_mul_i32 s15, s14, s12
	s_sub_i32 s8, s8, s15
	s_add_i32 s22, s14, 1
	s_sub_i32 s15, s8, s12
	s_cmp_ge_u32 s8, s12
	s_cselect_b32 s14, s22, s14
	s_cselect_b32 s8, s15, s8
	s_add_i32 s15, s14, 1
	s_cmp_ge_u32 s8, s12
	s_cselect_b32 s8, s15, s14
	s_xor_b32 s8, s8, s13
	s_sub_i32 s8, s8, s13
	s_mul_i32 s11, s8, s11
	s_sub_i32 s9, s9, s11
	s_add_i32 s10, s10, s9

;     __host__ __device__ bool next(int i, Unit& u) const {
;         const long L = (long)i * G + c; if (L >= nwg) return false;
;         int wgid = (int)L; { const int q = nwg / NXCD, r = nwg % NXCD, xcd = wgid % NXCD, off = wgid / NXCD; wgid = (xcd < r ? xcd * (q + 1) : r * (q + 1) + (xcd - r) * q) + off; }
;         const int nig = WGM * nN, gid = wgid / nig, fm = gid * WGM, gsz = (nM - fm) < WGM ? (nM - fm) : WGM;
;         u.pm = fm + ((wgid % nig) % gsz); u.pn = (wgid % nig) / gsz; return true;
;     }
.LBB0_156:
	s_add_i32 s34, s34, 1
	s_mul_i32 s4, s34, s75
	s_mul_hi_u32 s5, s34, s74
	s_add_i32 s5, s5, s4
	s_mul_i32 s4, s34, s74
	s_add_u32 s4, s4, s22
	s_addc_u32 s5, s5, s35
	v_cmp_gt_i64_e32 vcc, s[4:5], v[148:149]
	v_cmp_lt_i64_e64 s[6:7], s[4:5], v[146:147]
	s_cbranch_vccnz .LBB0_162
	s_cmp_eq_u32 s74, 0x100
	s_cbranch_scc0 .Lsched_slow_1
	s_mov_b32 s44, s45
	s_add_i32 s42, s50, 4
	s_branch .LBB0_162
.Lsched_slow_1:
	s_ashr_i32 s5, s4, 31
	s_lshr_b32 s5, s5, 29
	s_add_i32 s12, s4, s5
	s_and_b32 s5, s12, -8
	s_sub_i32 s13, s4, s5
	s_cmp_gt_i32 s13, -1
	s_mov_b64 s[4:5], -1
	s_cbranch_scc0 .LBB0_159
	s_lshl_b32 s18, s13, 6
	s_mov_b64 s[4:5], 0

;     __host__ __device__ bool next(int i, Unit& u) const {
;         const long L = (long)i * G + c; if (L >= nwg) return false;
;         int wgid = (int)L; { const int q = nwg / NXCD, r = nwg % NXCD, xcd = wgid % NXCD, off = wgid / NXCD; wgid = (xcd < r ? xcd * (q + 1) : r * (q + 1) + (xcd - r) * q) + off; }
;         const int nig = WGM * nN, gid = wgid / nig, fm = gid * WGM, gsz = (nM - fm) < WGM ? (nM - fm) : WGM;
;         u.pm = fm + ((wgid % nig) % gsz); u.pn = (wgid % nig) / gsz; return true;
;     }
.LBB0_248:
	s_add_i32 s42, s42, 1
	s_mul_i32 s2, s42, s75
	s_mul_hi_u32 s3, s42, s74
	s_add_i32 s3, s3, s2
	s_mul_i32 s2, s42, s74
	s_add_u32 s12, s2, s24
	s_addc_u32 s13, s3, s28
	v_mov_b64_e32 v[4:5], 0x500
	v_cmp_lt_i64_e64 s[2:3], s[12:13], v[4:5]
	v_mov_b64_e32 v[4:5], 0x4ff
	v_cmp_gt_i64_e32 vcc, s[12:13], v[4:5]
	s_cbranch_vccnz .LBB0_250
	s_cmp_eq_u32 s74, 0x100
	s_cbranch_scc0 .Lsched_slow_2
	s_mov_b32 s10, s16
	s_add_i32 s6, s44, 4
	s_branch .LBB0_250
.Lsched_slow_2:
	s_ashr_i32 s6, s12, 31
	s_lshr_b32 s6, s6, 29
	s_add_i32 s6, s12, s6
	s_ashr_i32 s7, s6, 3
	s_and_b32 s6, s6, -8
	s_sub_i32 s6, s12, s6
	s_cmp_lt_i32 s6, 0
	s_movk_i32 s10, 0xa1
	s_cselect_b32 s10, s10, 0xa0
	s_mul_i32 s6, s6, s10
	s_add_i32 s6, s6, s7
	s_mul_hi_i32 s7, s6, 0x66666667
	s_lshr_b32 s10, s7, 31
	s_ashr_i32 s7, s7, 6
	s_add_i32 s7, s7, s10
	s_lshl_b32 s10, s7, 3
	s_sub_i32 s11, 64, s10
	s_min_i32 s11, s11, 8
	s_abs_i32 s12, s11
	v_cvt_f32_u32_e32 v4, s12
	s_sub_i32 s14, 0, s12
	s_mulk_i32 s7, 0xa0
	s_sub_i32 s7, s6, s7
	v_rcp_iflag_f32_e32 v4, v4
	s_abs_i32 s6, s7
	s_xor_b32 s13, s7, s11
	s_ashr_i32 s13, s13, 31
	v_mul_f32_e32 v4, 0x4f7ffffe, v4
	v_cvt_u32_f32_e32 v4, v4
	s_nop 0
	v_readfirstlane_b32 s15, v4
	s_mul_i32 s14, s14, s15
	s_mul_hi_u32 s14, s15, s14
	s_add_i32 s15, s15, s14
	s_mul_hi_u32 s14, s6, s15
	s_mul_i32 s15, s14, s12
	s_sub_i32 s6, s6, s15
	s_add_i32 s22, s14, 1
	s_sub_i32 s15, s6, s12
	s_cmp_ge_u32 s6, s12
	s_cselect_b32 s14, s22, s14
	s_cselect_b32 s6, s15, s6
	s_add_i32 s15, s14, 1
	s_cmp_ge_u32 s6, s12
	s_cselect_b32 s6, s15, s14
	s_xor_b32 s6, s6, s13
	s_sub_i32 s6, s6, s13
	s_mul_i32 s11, s6, s11
	s_sub_i32 s7, s7, s11
	s_add_i32 s10, s10, s7

;     __host__ __device__ bool next(int i, Unit& u) const {
;         const long L = (long)i * G + c; if (L >= nwg) return false;
;         int wgid = (int)L; { const int q = nwg / NXCD, r = nwg % NXCD, xcd = wgid % NXCD, off = wgid / NXCD; wgid = (xcd < r ? xcd * (q + 1) : r * (q + 1) + (xcd - r) * q) + off; }
;         const int nig = WGM * nN, gid = wgid / nig, fm = gid * WGM, gsz = (nM - fm) < WGM ? (nM - fm) : WGM;
;         u.pm = fm + ((wgid % nig) % gsz); u.pn = (wgid % nig) / gsz; return true;
;     }
.LBB0_476:
	s_add_i32 s50, s50, 1
	s_mul_i32 s4, s50, s75
	s_mul_hi_u32 s5, s50, s74
	s_add_i32 s5, s5, s4
	s_mul_i32 s4, s50, s74
	s_add_u32 s14, s4, s28
	s_addc_u32 s15, s5, s51
	v_cmp_gt_i64_e32 vcc, s[14:15], v[148:149]
	v_cmp_lt_i64_e64 s[4:5], s[14:15], v[146:147]
	s_cbranch_vccnz .LBB0_482
	s_cmp_eq_u32 s74, 0x100
	s_cbranch_scc0 .Lsched_slow_3
	s_mov_b32 s12, s18
	s_add_i32 s10, s20, 4
	s_branch .LBB0_482
.Lsched_slow_3:
	s_ashr_i32 s10, s14, 31
	s_lshr_b32 s10, s10, 29
	s_add_i32 s12, s14, s10
	s_and_b32 s10, s12, -8
	s_sub_i32 s13, s14, s10
	s_cmp_gt_i32 s13, -1
	s_mov_b64 s[10:11], -1
	s_cbranch_scc0 .LBB0_479
	s_lshl_b32 s14, s13, 6
	s_mov_b64 s[10:11], 0

;     __host__ __device__ bool next(int i, Unit& u) const {
;         const long L = (long)i * G + c; if (L >= nwg) return false;
;         int wgid = (int)L; { const int q = nwg / NXCD, r = nwg % NXCD, xcd = wgid % NXCD, off = wgid / NXCD; wgid = (xcd < r ? xcd * (q + 1) : r * (q + 1) + (xcd - r) * q) + off; }
;         const int nig = WGM * nN, gid = wgid / nig, fm = gid * WGM, gsz = (nM - fm) < WGM ? (nM - fm) : WGM;
;         u.pm = fm + ((wgid % nig) % gsz); u.pn = (wgid % nig) / gsz; return true;
;     }
.LBB0_564:
	s_add_i32 s44, s44, 1
	s_mul_i32 s2, s44, s75
	s_mul_hi_u32 s3, s44, s74
	s_add_i32 s3, s3, s2
	s_mul_i32 s2, s44, s74
	s_add_u32 s12, s2, s24
	s_addc_u32 s13, s3, s28
	v_cmp_gt_i64_e32 vcc, s[12:13], v[144:145]
	v_cmp_lt_i64_e64 s[2:3], s[12:13], v[142:143]
	s_cbranch_vccnz .LBB0_566
	s_cmp_eq_u32 s74, 0x100
	s_cbranch_scc0 .Lsched_slow_4
	s_mov_b32 s10, s16
	s_add_i32 s8, s17, 4
	s_branch .LBB0_566
